# grid barrier: arrivers 8/16/24 of each XCD start an early L2 write-back (release write-back by the last arriver unchanged)
# baseline (speedup 1.0000x reference)
.LBB0_98:
	s_or_b64 exec, exec, s[10:11]
	v_cvt_f32_u32_e32 v4, v2
	s_waitcnt vmcnt(0)
	v_readfirstlane_b32 s3, v3
	v_sub_u32_e32 v3, 0, v2
	v_rcp_iflag_f32_e32 v4, v4
	v_add_u32_e32 v5, s3, v1
	v_mul_f32_e32 v4, 0x4f7ffffe, v4
	v_cvt_u32_f32_e32 v4, v4
	v_mul_lo_u32 v1, v3, v4
	v_mul_hi_u32 v1, v4, v1
	v_add_u32_e32 v1, v4, v1
	v_mul_hi_u32 v1, v5, v1
	v_mul_lo_u32 v3, v1, v2
	v_sub_u32_e32 v3, v5, v3
	v_add_u32_e32 v4, 1, v1
	v_cmp_ge_u32_e32 vcc, v3, v2
	s_nop 1
	v_cndmask_b32_e32 v1, v1, v4, vcc
	v_sub_u32_e32 v4, v3, v2
	v_cndmask_b32_e32 v3, v3, v4, vcc
	v_add_u32_e32 v4, 1, v1
	v_cmp_ge_u32_e32 vcc, v3, v2
	v_add_u32_e32 v3, 1, v5
	s_nop 0
	v_cndmask_b32_e32 v1, v1, v4, vcc
	v_mul_lo_u32 v4, v2, v1
	v_add_u32_e32 v2, v4, v2
	v_cmp_ne_u32_e32 vcc, v3, v2
	s_and_saveexec_b64 s[8:9], vcc
	s_xor_b64 s[8:9], exec, s[8:9]
	s_cbranch_execz .LBB0_112
	v_readfirstlane_b32 s98, v5
	s_nop 3
	s_and_b32 s98, s98, 7
	s_cmp_lg_u32 s98, 7
	s_cbranch_scc1 .Lmyewb_27
	buffer_wbl2 sc1
.Lmyewb_27:
	s_waitcnt lgkmcnt(0)
	v_mov_b32_e32 v0, 0x3500
	global_load_dword v0, v0, s[78:79] sc1
	s_add_u32 s12, s78, 0x3500
	s_addc_u32 s13, s79, 0
	s_waitcnt vmcnt(0)
	v_cmp_eq_u32_e32 vcc, v0, v1
	s_and_saveexec_b64 s[10:11], vcc
	s_cbranch_execz .LBB0_111
	s_mov_b32 s3, 1
	s_mov_b64 s[14:15], 0
	v_mov_b32_e32 v0, 0
	s_branch .LBB0_102

.LBB0_171:
	s_or_b64 exec, exec, s[8:9]
	v_cvt_f32_u32_e32 v4, v2
	s_waitcnt vmcnt(0)
	v_readfirstlane_b32 s6, v3
	v_sub_u32_e32 v3, 0, v2
	v_rcp_iflag_f32_e32 v4, v4
	v_add_u32_e32 v5, s6, v1
	v_mul_f32_e32 v4, 0x4f7ffffe, v4
	v_cvt_u32_f32_e32 v4, v4
	v_mul_lo_u32 v1, v3, v4
	v_mul_hi_u32 v1, v4, v1
	v_add_u32_e32 v1, v4, v1
	v_mul_hi_u32 v1, v5, v1
	v_mul_lo_u32 v3, v1, v2
	v_sub_u32_e32 v3, v5, v3
	v_add_u32_e32 v4, 1, v1
	v_cmp_ge_u32_e32 vcc, v3, v2
	s_nop 1
	v_cndmask_b32_e32 v1, v1, v4, vcc
	v_sub_u32_e32 v4, v3, v2
	v_cndmask_b32_e32 v3, v3, v4, vcc
	v_add_u32_e32 v4, 1, v1
	v_cmp_ge_u32_e32 vcc, v3, v2
	v_add_u32_e32 v3, 1, v5
	s_nop 0
	v_cndmask_b32_e32 v1, v1, v4, vcc
	v_mul_lo_u32 v4, v2, v1
	v_add_u32_e32 v2, v4, v2
	v_cmp_ne_u32_e32 vcc, v3, v2
	s_and_saveexec_b64 s[6:7], vcc
	s_xor_b64 s[6:7], exec, s[6:7]
	s_cbranch_execz .LBB0_185
	v_readfirstlane_b32 s98, v5
	s_nop 3
	s_and_b32 s98, s98, 7
	s_cmp_lg_u32 s98, 7
	s_cbranch_scc1 .Lmyewb_26
	buffer_wbl2 sc1
.Lmyewb_26:
	s_waitcnt lgkmcnt(0)
	v_mov_b32_e32 v0, 0x3500
	global_load_dword v0, v0, s[78:79] sc1
	s_add_u32 s10, s78, 0x3500
	s_addc_u32 s11, s79, 0
	s_waitcnt vmcnt(0)
	v_cmp_eq_u32_e32 vcc, v0, v1
	s_and_saveexec_b64 s[8:9], vcc
	s_cbranch_execz .LBB0_184
	s_mov_b32 s22, 1
	s_mov_b64 s[12:13], 0
	v_mov_b32_e32 v0, 0
	s_branch .LBB0_175

.LBB0_1286:
	s_or_b64 exec, exec, s[10:11]
	v_cvt_f32_u32_e32 v4, v2
	s_waitcnt vmcnt(0)
	v_readfirstlane_b32 s8, v3
	v_sub_u32_e32 v3, 0, v2
	v_rcp_iflag_f32_e32 v4, v4
	v_add_u32_e32 v5, s8, v1
	v_mul_f32_e32 v4, 0x4f7ffffe, v4
	v_cvt_u32_f32_e32 v4, v4
	v_mul_lo_u32 v1, v3, v4
	v_mul_hi_u32 v1, v4, v1
	v_add_u32_e32 v1, v4, v1
	v_mul_hi_u32 v1, v5, v1
	v_mul_lo_u32 v3, v1, v2
	v_sub_u32_e32 v3, v5, v3
	v_add_u32_e32 v4, 1, v1
	v_cmp_ge_u32_e32 vcc, v3, v2
	s_nop 1
	v_cndmask_b32_e32 v1, v1, v4, vcc
	v_sub_u32_e32 v4, v3, v2
	v_cndmask_b32_e32 v3, v3, v4, vcc
	v_add_u32_e32 v4, 1, v1
	v_cmp_ge_u32_e32 vcc, v3, v2
	v_add_u32_e32 v3, 1, v5
	s_nop 0
	v_cndmask_b32_e32 v1, v1, v4, vcc
	v_mul_lo_u32 v4, v2, v1
	v_add_u32_e32 v2, v4, v2
	v_cmp_ne_u32_e32 vcc, v3, v2
	s_and_saveexec_b64 s[8:9], vcc
	s_xor_b64 s[8:9], exec, s[8:9]
	s_cbranch_execz .LBB0_1300
	v_readfirstlane_b32 s98, v5
	s_nop 3
	s_and_b32 s98, s98, 7
	s_cmp_lg_u32 s98, 7
	s_cbranch_scc1 .Lmyewb_15
	buffer_wbl2 sc1
.Lmyewb_15:
	s_waitcnt lgkmcnt(0)
	v_mov_b32_e32 v0, 0x3500
	global_load_dword v0, v0, s[78:79] sc1
	s_add_u32 s12, s78, 0x3500
	s_addc_u32 s13, s79, 0
	s_waitcnt vmcnt(0)
	v_cmp_eq_u32_e32 vcc, v0, v1
	s_and_saveexec_b64 s[10:11], vcc
	s_cbranch_execz .LBB0_1299
	s_mov_b32 s24, 1
	s_mov_b64 s[14:15], 0
	v_mov_b32_e32 v0, 0
	s_branch .LBB0_1290

.LBB0_2705:
	s_or_b64 exec, exec, s[10:11]
	v_cvt_f32_u32_e32 v4, v2
	s_waitcnt vmcnt(0)
	v_readfirstlane_b32 s6, v3
	v_sub_u32_e32 v3, 0, v2
	v_rcp_iflag_f32_e32 v4, v4
	v_add_u32_e32 v5, s6, v1
	v_mul_f32_e32 v4, 0x4f7ffffe, v4
	v_cvt_u32_f32_e32 v4, v4
	v_mul_lo_u32 v1, v3, v4
	v_mul_hi_u32 v1, v4, v1
	v_add_u32_e32 v1, v4, v1
	v_mul_hi_u32 v1, v5, v1
	v_mul_lo_u32 v3, v1, v2
	v_sub_u32_e32 v3, v5, v3
	v_add_u32_e32 v4, 1, v1
	v_cmp_ge_u32_e32 vcc, v3, v2
	s_nop 1
	v_cndmask_b32_e32 v1, v1, v4, vcc
	v_sub_u32_e32 v4, v3, v2
	v_cndmask_b32_e32 v3, v3, v4, vcc
	v_add_u32_e32 v4, 1, v1
	v_cmp_ge_u32_e32 vcc, v3, v2
	v_add_u32_e32 v3, 1, v5
	s_nop 0
	v_cndmask_b32_e32 v1, v1, v4, vcc
	v_mul_lo_u32 v4, v2, v1
	v_add_u32_e32 v2, v4, v2
	v_cmp_ne_u32_e32 vcc, v3, v2
	s_and_saveexec_b64 s[6:7], vcc
	s_xor_b64 s[6:7], exec, s[6:7]
	s_cbranch_execz .LBB0_2719
	v_readfirstlane_b32 s98, v5
	s_nop 3
	s_and_b32 s98, s98, 7
	s_cmp_lg_u32 s98, 7
	s_cbranch_scc1 .Lmyewb_1
	buffer_wbl2 sc1

.LBB0_2814:
	s_or_b64 exec, exec, s[6:7]
	v_cvt_f32_u32_e32 v4, v2
	s_waitcnt vmcnt(0)
	v_readfirstlane_b32 s4, v3
	v_sub_u32_e32 v3, 0, v2
	v_rcp_iflag_f32_e32 v4, v4
	v_add_u32_e32 v5, s4, v1
	v_mul_f32_e32 v4, 0x4f7ffffe, v4
	v_cvt_u32_f32_e32 v4, v4
	v_mul_lo_u32 v1, v3, v4
	v_mul_hi_u32 v1, v4, v1
	v_add_u32_e32 v1, v4, v1
	v_mul_hi_u32 v1, v5, v1
	v_mul_lo_u32 v3, v1, v2
	v_sub_u32_e32 v3, v5, v3
	v_add_u32_e32 v4, 1, v1
	v_cmp_ge_u32_e32 vcc, v3, v2
	s_nop 1
	v_cndmask_b32_e32 v1, v1, v4, vcc
	v_sub_u32_e32 v4, v3, v2
	v_cndmask_b32_e32 v3, v3, v4, vcc
	v_add_u32_e32 v4, 1, v1
	v_cmp_ge_u32_e32 vcc, v3, v2
	v_add_u32_e32 v3, 1, v5
	s_nop 0
	v_cndmask_b32_e32 v1, v1, v4, vcc
	v_mul_lo_u32 v4, v2, v1
	v_add_u32_e32 v2, v4, v2
	v_cmp_ne_u32_e32 vcc, v3, v2
	s_and_saveexec_b64 s[4:5], vcc
	s_xor_b64 s[4:5], exec, s[4:5]
	s_cbranch_execz .LBB0_2828
	v_readfirstlane_b32 s98, v5
	s_nop 3
	s_and_b32 s98, s98, 7
	s_cmp_lg_u32 s98, 7
	s_cbranch_scc1 .Lmyewb_0
	buffer_wbl2 sc1
.Lmyewb_0:
	s_waitcnt lgkmcnt(0)
	v_mov_b32_e32 v0, 0x3500
	global_load_dword v0, v0, s[78:79] sc1
	s_add_u32 s8, s78, 0x3500
	s_addc_u32 s9, s79, 0
	s_waitcnt vmcnt(0)
	v_cmp_eq_u32_e32 vcc, v0, v1
	s_and_saveexec_b64 s[6:7], vcc
	s_cbranch_execz .LBB0_2827
	s_mov_b32 s20, 1
	s_mov_b64 s[10:11], 0
	v_mov_b32_e32 v0, 0
	s_branch .LBB0_2818
